# v36 plus early L1 invalidate in the two prologue grid barriers
# speedup vs baseline: 1.0038x; 1.0038x over previous
.LBB0_180:
	s_or_b64 exec, exec, s[8:9]
	s_waitcnt lgkmcnt(1)
	v_cvt_f32_u32_e32 v4, v2
	s_waitcnt vmcnt(0)
	v_readfirstlane_b32 s4, v3
	buffer_inv sc1
	v_sub_u32_e32 v3, 0, v2
	v_rcp_iflag_f32_e32 v4, v4
	v_add_u32_e32 v5, s4, v1
	v_mul_f32_e32 v4, 0x4f7ffffe, v4
	v_cvt_u32_f32_e32 v4, v4
	v_mul_lo_u32 v1, v3, v4
	v_mul_hi_u32 v1, v4, v1
	v_add_u32_e32 v1, v4, v1
	v_mul_hi_u32 v1, v5, v1
	v_mul_lo_u32 v3, v1, v2
	v_sub_u32_e32 v3, v5, v3
	v_add_u32_e32 v4, 1, v1
	v_cmp_ge_u32_e32 vcc, v3, v2
	s_nop 1
	v_cndmask_b32_e32 v1, v1, v4, vcc
	v_sub_u32_e32 v4, v3, v2
	v_cndmask_b32_e32 v3, v3, v4, vcc
	v_add_u32_e32 v4, 1, v1
	v_cmp_ge_u32_e32 vcc, v3, v2
	v_add_u32_e32 v3, 1, v5
	s_nop 0
	v_cndmask_b32_e32 v1, v1, v4, vcc
	v_mul_lo_u32 v4, v2, v1
	v_add_u32_e32 v2, v4, v2
	v_cmp_ne_u32_e32 vcc, v3, v2
	s_and_saveexec_b64 s[4:5], vcc
	s_xor_b64 s[4:5], exec, s[4:5]
	s_cbranch_execz .LBB0_194
	s_add_i32 s6, s30, 0x900
	s_mov_b32 s7, 0
	s_lshl_b64 s[6:7], s[6:7], 2
	v_readlane_b32 s8, v254, 10
	v_readlane_b32 s9, v254, 11
	s_add_u32 s10, s8, s6
	s_addc_u32 s11, s9, s7
	s_waitcnt lgkmcnt(0)
	v_mov_b32_e32 v0, 0
	global_load_dword v2, v0, s[10:11] sc1
	s_waitcnt vmcnt(0)
	v_cmp_eq_u32_e32 vcc, v2, v1
	s_and_saveexec_b64 s[6:7], vcc
	s_cbranch_execz .LBB0_193
	s_add_u32 s8, s40, 0x4200
	s_addc_u32 s9, s41, 0
	s_mov_b32 s31, 1
	s_mov_b64 s[12:13], 0
	s_branch .LBB0_184

.LBB0_190:
	s_or_b64 exec, exec, s[12:13]
	s_xor_b64 s[10:11], s[20:21], -1
	s_and_saveexec_b64 s[12:13], s[10:11]
	s_xor_b64 s[12:13], exec, s[12:13]
	s_cbranch_execz .LBB0_193
	s_mov_b64 s[10:11], exec
	v_mbcnt_lo_u32_b32 v0, s10, 0
	v_mbcnt_hi_u32_b32 v0, s11, v0
	v_cmp_eq_u32_e32 vcc, 0, v0
	s_and_b64 s[12:13], exec, vcc
	s_mov_b64 exec, s[12:13]
	s_cbranch_execz .LBB0_193
	s_bcnt1_i32_b64 s10, s[10:11]
	v_mov_b32_e32 v0, 0
	v_mov_b32_e32 v1, s10
	global_atomic_add v0, v1, s[8:9]
.LBB0_193:
	s_or_b64 exec, exec, s[6:7]
	s_waitcnt vmcnt(0)
	s_waitcnt vmcnt(0)
.LBB0_194:
	s_andn2_saveexec_b64 s[4:5], s[4:5]
	s_cbranch_execz .LBB0_214
	s_mov_b64 s[4:5], exec
	buffer_wbl2 sc1
	s_waitcnt lgkmcnt(0)
	s_waitcnt vmcnt(0)
	v_mbcnt_lo_u32_b32 v1, s4, 0
	v_mbcnt_hi_u32_b32 v1, s5, v1
	v_cmp_eq_u32_e32 vcc, 0, v1
	s_and_saveexec_b64 s[6:7], vcc
	s_cbranch_execz .LBB0_197
	s_bcnt1_i32_b64 s4, s[4:5]
	v_mov_b32_e32 v2, 0x7000
	v_mov_b32_e32 v3, s4
	global_atomic_add v2, v2, v3, s[40:41] offset:1024 sc0

.LBB0_211:
	s_or_b64 exec, exec, s[4:5]
	s_mov_b64 s[4:5], exec
	v_mbcnt_lo_u32_b32 v0, s4, 0
	v_mbcnt_hi_u32_b32 v0, s5, v0
	s_mov_b32 s9, 0
	v_cmp_eq_u32_e32 vcc, 0, v0
	s_waitcnt vmcnt(0)
	s_and_saveexec_b64 s[6:7], vcc
	s_cbranch_execz .LBB0_213
	s_add_i32 s8, s30, 0x900
	s_lshl_b64 s[8:9], s[8:9], 2
	v_readlane_b32 s10, v254, 10
	v_readlane_b32 s11, v254, 11
	s_add_u32 s8, s10, s8
	s_addc_u32 s9, s11, s9
	s_bcnt1_i32_b64 s4, s[4:5]
	v_mov_b32_e32 v0, 0
	v_mov_b32_e32 v1, s4
	global_atomic_add v0, v1, s[8:9]

.LBB0_418:
	s_or_b64 exec, exec, s[8:9]
	s_waitcnt lgkmcnt(1)
	v_cvt_f32_u32_e32 v4, v2
	s_waitcnt vmcnt(0)
	v_readfirstlane_b32 s4, v3
	buffer_inv sc1
	v_sub_u32_e32 v3, 0, v2
	v_rcp_iflag_f32_e32 v4, v4
	v_add_u32_e32 v5, s4, v1
	v_mul_f32_e32 v4, 0x4f7ffffe, v4
	v_cvt_u32_f32_e32 v4, v4
	v_mul_lo_u32 v1, v3, v4
	v_mul_hi_u32 v1, v4, v1
	v_add_u32_e32 v1, v4, v1
	v_mul_hi_u32 v1, v5, v1
	v_mul_lo_u32 v3, v1, v2
	v_sub_u32_e32 v3, v5, v3
	v_add_u32_e32 v4, 1, v1
	v_cmp_ge_u32_e32 vcc, v3, v2
	s_nop 1
	v_cndmask_b32_e32 v1, v1, v4, vcc
	v_sub_u32_e32 v4, v3, v2
	v_cndmask_b32_e32 v3, v3, v4, vcc
	v_add_u32_e32 v4, 1, v1
	v_cmp_ge_u32_e32 vcc, v3, v2
	v_add_u32_e32 v3, 1, v5
	s_nop 0
	v_cndmask_b32_e32 v1, v1, v4, vcc
	v_mul_lo_u32 v4, v2, v1
	v_add_u32_e32 v2, v4, v2
	v_cmp_ne_u32_e32 vcc, v3, v2
	s_and_saveexec_b64 s[4:5], vcc
	s_xor_b64 s[4:5], exec, s[4:5]
	s_cbranch_execz .LBB0_432
	s_add_i32 s6, s22, 0x900
	s_mov_b32 s7, 0
	s_lshl_b64 s[6:7], s[6:7], 2
	v_readlane_b32 s8, v254, 10
	v_readlane_b32 s9, v254, 11
	s_add_u32 s10, s8, s6
	s_addc_u32 s11, s9, s7
	s_waitcnt lgkmcnt(0)
	v_mov_b32_e32 v0, 0
	global_load_dword v2, v0, s[10:11] sc1
	s_waitcnt vmcnt(0)
	v_cmp_eq_u32_e32 vcc, v2, v1
	s_and_saveexec_b64 s[6:7], vcc
	s_cbranch_execz .LBB0_431
	s_add_u32 s8, s40, 0x4200
	s_addc_u32 s9, s41, 0
	s_mov_b32 s23, 1
	s_mov_b64 s[12:13], 0
	s_branch .LBB0_422

.LBB0_428:
	s_or_b64 exec, exec, s[12:13]
	s_xor_b64 s[10:11], s[14:15], -1
	s_and_saveexec_b64 s[12:13], s[10:11]
	s_xor_b64 s[12:13], exec, s[12:13]
	s_cbranch_execz .LBB0_431
	s_mov_b64 s[10:11], exec
	v_mbcnt_lo_u32_b32 v0, s10, 0
	v_mbcnt_hi_u32_b32 v0, s11, v0
	v_cmp_eq_u32_e32 vcc, 0, v0
	s_and_b64 s[12:13], exec, vcc
	s_mov_b64 exec, s[12:13]
	s_cbranch_execz .LBB0_431
	s_bcnt1_i32_b64 s10, s[10:11]
	v_mov_b32_e32 v0, 0
	v_mov_b32_e32 v1, s10
	global_atomic_add v0, v1, s[8:9]
.LBB0_431:
	s_or_b64 exec, exec, s[6:7]
	s_waitcnt vmcnt(0)
	s_waitcnt vmcnt(0)
.LBB0_432:
	s_andn2_saveexec_b64 s[4:5], s[4:5]
	s_cbranch_execz .LBB0_452
	s_mov_b64 s[4:5], exec
	buffer_wbl2 sc1
	s_waitcnt lgkmcnt(0)
	s_waitcnt vmcnt(0)
	v_mbcnt_lo_u32_b32 v1, s4, 0
	v_mbcnt_hi_u32_b32 v1, s5, v1
	v_cmp_eq_u32_e32 vcc, 0, v1
	s_and_saveexec_b64 s[6:7], vcc
	s_cbranch_execz .LBB0_435
	s_bcnt1_i32_b64 s4, s[4:5]
	v_mov_b32_e32 v2, 0x7000
	v_mov_b32_e32 v3, s4
	global_atomic_add v2, v2, v3, s[40:41] offset:1024 sc0

.LBB0_449:
	s_or_b64 exec, exec, s[4:5]
	s_mov_b64 s[4:5], exec
	v_mbcnt_lo_u32_b32 v0, s4, 0
	v_mbcnt_hi_u32_b32 v0, s5, v0
	s_mov_b32 s9, 0
	v_cmp_eq_u32_e32 vcc, 0, v0
	s_waitcnt vmcnt(0)
	s_and_saveexec_b64 s[6:7], vcc
	s_cbranch_execz .LBB0_451
	s_add_i32 s8, s22, 0x900
	s_lshl_b64 s[8:9], s[8:9], 2
	v_readlane_b32 s10, v254, 10
	v_readlane_b32 s11, v254, 11
	s_add_u32 s8, s10, s8
	s_addc_u32 s9, s11, s9
	s_bcnt1_i32_b64 s4, s[4:5]
	v_mov_b32_e32 v0, 0
	v_mov_b32_e32 v1, s4
	global_atomic_add v0, v1, s[8:9]
